# attention merge segment: the partner-half O reads (4 ds_read_b64) issued together up front with counted lgkmcnt waits
# baseline (speedup 1.0000x reference)
; __device__ __forceinline__ unsigned cvt_pk_bf16(float lo, float hi) { unsigned r; asm volatile("v_cvt_pk_bf16_f32 %0, %1, %2" : "=v"(r) : "v"(lo), "v"(hi)); return r; }
; __device__ __forceinline__ float bf_lo(unsigned w) { return __uint_as_float(w << 16); }
; __device__ __forceinline__ float bf_hi(unsigned w) { return __uint_as_float(w & 0xffff0000u); }
; __device__ __forceinline__ float fast_exp2(float x) { return __builtin_amdgcn_exp2f(x); }
; __device__ __forceinline__ void attn_phase(const bf16_t* Q, const bf16_t* Kb, const bf16_t* VTa, const float* rpb, bf16_t* Y, LAS unsigned char* lds, int bx, int G, int tid, int wave, int lane) {
;     ...
;             if (hf == 0) {
;                 const float m1 = ml[0], l1 = ml[1];
;                 const float m = fmaxf(mx, m1), sc0 = fast_exp2((mx - m) * 1.4426950409f), sc1 = fast_exp2((m1 - m) * 1.4426950409f);
;                 const float inv = 1.0f / (l * sc0 + l1 * sc1);
;                 bf16_t* yp = Y + (size_t)(r * 64 + c) * 2048 + 1024 + h * 64 + 4 * fq;
; #pragma unroll
;                 for (int dt = 0; dt < 4; ++dt) { const u32x2 pw = ol[dt]; const f32x4 o1 = {bf_lo(pw.x), bf_hi(pw.x), bf_lo(pw.y), bf_hi(pw.y)}; const f32x4 v = (o[dt] * sc0 + o1 * sc1) * inv;
;                     u32x2 w; w.x = cvt_pk_bf16(v[0], v[1]); w.y = cvt_pk_bf16(v[2], v[3]); *(u32x2*)(yp + 16 * dt) = w; }
;             }
.LBB0_459:
	s_waitcnt lgkmcnt(0)
	s_barrier
	v_cndmask_b32_e64 v26, 0, 1, s[12:13]
	v_cmp_ne_u32_e64 s[56:57], 1, v26
	s_andn2_b64 vcc, exec, s[12:13]
	s_cbranch_vccnz .LBB0_461
	v_add_u32_e32 v26, 0, v57
	v_add_u32_e32 v26, 0x20800, v26
	ds_read_b64 v[26:27], v26
	v_add_u32_e32 v28, 0, v59
	v_add_u32_e32 v63, 0x21000, v28
	v_max_f32_e32 v35, v32, v32
	ds_read_b64 v[28:29], v63
	ds_read_b64 v[222:223], v63 offset:8
	ds_read_b64 v[224:225], v63 offset:16
	ds_read_b64 v[226:227], v63 offset:24
	s_waitcnt lgkmcnt(3)
	v_max_f32_e32 v36, v26, v26
	v_max_f32_e32 v35, v35, v36
	v_sub_f32_e32 v32, v32, v35
	v_sub_f32_e32 v26, v26, v35
	v_mul_f32_e32 v32, 0x3fb8aa3b, v32
	v_mul_f32_e32 v26, 0x3fb8aa3b, v26
	v_exp_f32_e32 v36, v32
	v_exp_f32_e32 v37, v26
	v_mov_b32_e32 v26, v33
	v_ashrrev_i32_e32 v99, 31, v98
	v_pk_mul_f32 v[26:27], v[26:27], v[36:37]
	s_nop 0
	v_add_f32_e32 v26, v26, v27
	v_div_scale_f32 v27, vcc, v26, v26, 1.0
	v_rcp_f32_e32 v32, v27
	v_mov_b32_e32 v100, v37
	v_fma_f32 v33, -v27, v32, 1.0
	v_fmac_f32_e32 v32, v33, v32
	v_div_scale_f32 v33, vcc, 1.0, v26, 1.0
	v_mul_f32_e32 v35, v33, v32
	v_fma_f32 v65, -v27, v35, v33
	v_fmac_f32_e32 v35, v65, v32
	v_fma_f32 v27, -v27, v35, v33
	v_div_fmas_f32 v27, v27, v32, v35
	v_lshlrev_b32_e32 v32, 16, v28
	v_and_b32_e32 v33, 0xffff0000, v28
	v_lshlrev_b32_e32 v28, 16, v29
	v_and_b32_e32 v29, 0xffff0000, v29
	v_pk_mul_f32 v[28:29], v[100:101], v[28:29] op_sel_hi:[0,1]
	v_pk_mul_f32 v[32:33], v[100:101], v[32:33] op_sel_hi:[0,1]
	v_div_fixup_f32 v26, v27, v26, 1.0
	v_pk_fma_f32 v[22:23], v[22:23], v[36:37], v[32:33] op_sel_hi:[1,0,1]
	v_pk_fma_f32 v[24:25], v[24:25], v[36:37], v[28:29] op_sel_hi:[1,0,1]
	v_pk_mul_f32 v[22:23], v[26:27], v[22:23] op_sel_hi:[0,1]
	v_pk_mul_f32 v[24:25], v[26:27], v[24:25] op_sel_hi:[0,1]
	v_cvt_pk_bf16_f32 v22, v22, v23
	v_cvt_pk_bf16_f32 v23, v24, v25
	v_lshlrev_b64 v[28:29], 12, v[98:99]
	v_lshl_add_u64 v[28:29], v[94:95], 0, v[28:29]
	global_store_dwordx2 v[28:29], v[22:23], off offset:2048
	s_waitcnt lgkmcnt(2)
	v_lshlrev_b32_e32 v22, 16, v222
	v_and_b32_e32 v23, 0xffff0000, v222
	v_lshlrev_b32_e32 v24, 16, v223
	v_and_b32_e32 v25, 0xffff0000, v223
	v_pk_mul_f32 v[24:25], v[100:101], v[24:25] op_sel_hi:[0,1]
	v_pk_mul_f32 v[22:23], v[100:101], v[22:23] op_sel_hi:[0,1]
	v_pk_fma_f32 v[18:19], v[18:19], v[36:37], v[22:23] op_sel_hi:[1,0,1]
	v_pk_fma_f32 v[20:21], v[20:21], v[36:37], v[24:25] op_sel_hi:[1,0,1]
	v_pk_mul_f32 v[18:19], v[26:27], v[18:19] op_sel_hi:[0,1]
	v_pk_mul_f32 v[20:21], v[26:27], v[20:21] op_sel_hi:[0,1]
	v_cvt_pk_bf16_f32 v18, v18, v19
	v_cvt_pk_bf16_f32 v19, v20, v21
	global_store_dwordx2 v[28:29], v[18:19], off offset:2080
	s_waitcnt lgkmcnt(1)
	v_lshlrev_b32_e32 v18, 16, v224
	v_and_b32_e32 v19, 0xffff0000, v224
	v_lshlrev_b32_e32 v20, 16, v225
	v_and_b32_e32 v21, 0xffff0000, v225
	v_pk_mul_f32 v[20:21], v[100:101], v[20:21] op_sel_hi:[0,1]
	v_pk_mul_f32 v[18:19], v[100:101], v[18:19] op_sel_hi:[0,1]
	v_pk_fma_f32 v[14:15], v[14:15], v[36:37], v[18:19] op_sel_hi:[1,0,1]
	v_pk_fma_f32 v[16:17], v[16:17], v[36:37], v[20:21] op_sel_hi:[1,0,1]
	v_pk_mul_f32 v[14:15], v[26:27], v[14:15] op_sel_hi:[0,1]
	v_pk_mul_f32 v[16:17], v[26:27], v[16:17] op_sel_hi:[0,1]
	v_cvt_pk_bf16_f32 v14, v14, v15
	v_cvt_pk_bf16_f32 v15, v16, v17
	global_store_dwordx2 v[28:29], v[14:15], off offset:2112
	s_waitcnt lgkmcnt(0)
	v_lshlrev_b32_e32 v14, 16, v226
	v_and_b32_e32 v15, 0xffff0000, v226
	v_lshlrev_b32_e32 v16, 16, v227
	v_and_b32_e32 v17, 0xffff0000, v227
	v_pk_mul_f32 v[14:15], v[100:101], v[14:15] op_sel_hi:[0,1]
	v_pk_mul_f32 v[16:17], v[100:101], v[16:17] op_sel_hi:[0,1]
	v_pk_fma_f32 v[10:11], v[10:11], v[36:37], v[14:15] op_sel_hi:[1,0,1]
	v_pk_fma_f32 v[12:13], v[12:13], v[36:37], v[16:17] op_sel_hi:[1,0,1]
	v_pk_mul_f32 v[10:11], v[26:27], v[10:11] op_sel_hi:[0,1]
	v_pk_mul_f32 v[12:13], v[26:27], v[12:13] op_sel_hi:[0,1]
	v_cvt_pk_bf16_f32 v10, v10, v11
	v_cvt_pk_bf16_f32 v11, v12, v13
	global_store_dwordx2 v[28:29], v[10:11], off offset:2144
